# lever 1: GEMM phase prologues (QKV L1, Wo L1, up, down): compiler vmcnt(0) in the middle of the 8-piece LDS-DMA burst -> vmcnt(4) (only guards a WAW on v15 by older loads)
# speedup vs baseline: 1.0059x; 1.0047x over previous
; #define PG8_STAGE(bufoff, gbase, voff) do { _Pragma("unroll") for (int _i = 0; _i < 2; ++_i) \
;         __builtin_amdgcn_global_load_lds((const unsigned*)((const char*)(gbase) + (voff)[_i]), (PG8_LAS unsigned*)(lds + (bufoff) + ldsw + _i * 8192), 16, 0, 0); } while (0)
; #define PG8_BAR __builtin_amdgcn_s_barrier()
; template <class Epi, class Sched, bool ALIGN_EPI = false, bool SP2 = false>
; __device__ __forceinline__ void gemm_phase(PG8_LAS unsigned char* lds, const Gemm g, const Sched& S, const Epi& E) {
;     int tid_ = mk_tid(); asm volatile("" : "+v"(tid_));
;     const int tid = tid_, wid = __builtin_amdgcn_readfirstlane(tid >> 6), lane = tid & 63, wr = wid >> 2, wc = wid & 3, fr = lane & 15, fq = lane >> 4;
;     const int K = g.K, nt = K / BK;
;     unsigned voffA[2], voffB[2];
; #pragma unroll
;     for (int i = 0; i < 2; ++i) { int R, C; stage_rc(tid * 16 + i * 8192, R, C); const int Rb = Epi::PERM ? ((R & ~31) + perm32(R & 31)) : R;
;         voffA[i] = (unsigned)(R * K + C) * 2u; voffB[i] = (unsigned)(Rb * K + C) * 2u; }
;     const size_t kstep = (size_t)(BK * 2);
;     const size_t hstep = (size_t)HALF * K * 2;
;     const size_t tstep = 2 * hstep;
;     const unsigned ldsw = (unsigned)wid * 1024u;
;     const int aoff = lds_byte(wr * 64 + fr, fq * 8), boff = lds_byte(wc * 32 + fr, fq * 8);
;     ...
;         PG8_STAGE(PG8_SB(0, 0), cB, voffB); PG8_STAGE(PG8_SB(0, 1), cB + hstep, voffB); PG8_STAGE(PG8_SA(0, 0), cA, voffA); PG8_STAGE(PG8_SA(0, 1), cA + hstep, voffA);
;         if (wr == 1) PG8_BAR;
.LBB0_176:
	s_waitcnt lgkmcnt(0)
	s_barrier
	s_getreg_b32 s5, hwreg(HW_REG_HW_ID, 0, 6)
	s_and_b32 s5, s5, 63
	s_lshl_b32 s5, s5, 2
	s_or_b32 s5, s5, 0x25000
	v_mov_b32_e32 v1, s5
	ds_read_b32 v1, v1
	v_readlane_b32 s8, v253, 28
	v_mbcnt_lo_u32_b32 v2, -1, 0
	v_mbcnt_hi_u32_b32 v2, -1, v2
	v_readlane_b32 s9, v253, 29
	s_andn2_b64 vcc, exec, s[8:9]
	s_waitcnt lgkmcnt(0)
	v_readfirstlane_b32 s5, v1
	s_waitcnt vmcnt(5)
	s_nop 0
	v_lshl_add_u32 v12, s5, 6, v2
	s_nop 0
	v_readfirstlane_b32 s12, v12
	s_cbranch_vccnz .LBB0_258
	v_lshlrev_b32_e32 v1, 4, v12
	v_add_u32_e32 v2, 0x2000, v1
	v_ashrrev_i32_e32 v3, 31, v2
	v_lshrrev_b32_e32 v3, 22, v3
	v_add_u32_e32 v3, v2, v3
	v_ashrrev_i32_e32 v6, 10, v3
	v_mul_i32_i24_e32 v3, 0x400, v6
	v_sub_u32_e32 v2, v2, v3
	v_lshrrev_b32_e32 v3, 4, v2
	v_bitop3_b32 v2, v3, v2, 32 bitop3:0x6c
	v_ashrrev_i32_e32 v3, 31, v2
	v_lshrrev_b32_e32 v3, 26, v3
	v_add_u32_e32 v3, v2, v3
	v_lshlrev_b32_e32 v4, 3, v6
	v_ashrrev_i32_e32 v7, 6, v3
	v_and_b32_e32 v4, -16, v4
	v_add_u32_e32 v4, v7, v4
	v_and_b32_e32 v5, 3, v7
	s_mov_b32 s8, 0x1fffe0
	v_lshrrev_b32_e32 v8, 2, v4
	v_lshlrev_b32_e32 v9, 1, v4
	v_and_b32_e32 v3, 0xc0, v3
	v_and_or_b32 v5, v4, s8, v5
	v_and_b32_e32 v8, 4, v8
	v_and_b32_e32 v9, 24, v9
	v_sub_u32_e32 v2, v2, v3
	v_or3_b32 v5, v5, v8, v9
	v_lshlrev_b32_e32 v8, 5, v6
	v_ashrrev_i16_sdwa v2, v252, sext(v2) dst_sel:DWORD dst_unused:UNUSED_PAD src0_sel:DWORD src1_sel:BYTE_0
	v_and_b32_e32 v9, 32, v8
	v_bfe_i32 v8, v2, 0, 16
	v_add_lshl_u32 v2, v9, v8, 1
	v_lshl_add_u32 v14, v5, 11, v2
	v_lshl_add_u32 v166, v4, 11, v2
	v_bfe_i32 v2, v12, 27, 1
	v_lshrrev_b32_e32 v2, 22, v2
	v_add_u32_e32 v2, v1, v2
	v_and_b32_e32 v2, 0xfffffc00, v2
	v_sub_u32_e32 v1, v1, v2
	v_lshrrev_b32_e32 v2, 4, v1
	v_ashrrev_i32_e32 v3, 31, v12
	v_bitop3_b32 v1, v2, v1, 32 bitop3:0x6c
	v_lshrrev_b32_e32 v3, 26, v3
	v_ashrrev_i32_e32 v2, 31, v1
	v_add_u32_e32 v3, v12, v3
	v_lshrrev_b32_e32 v2, 26, v2
	v_ashrrev_i32_e32 v10, 6, v3
	v_add_u32_e32 v2, v1, v2
	v_lshlrev_b32_e32 v3, 3, v10
	v_ashrrev_i32_e32 v9, 6, v2
	v_and_b32_e32 v3, -16, v3
	v_add_u32_e32 v3, v9, v3
	v_and_b32_e32 v4, 3, v9
	v_lshrrev_b32_e32 v5, 2, v3
	v_lshlrev_b32_e32 v11, 1, v3
	v_and_b32_e32 v2, 0xc0, v2
	s_ashr_i32 s14, s12, 6
	v_and_or_b32 v4, v3, s8, v4
	v_and_b32_e32 v5, 4, v5
	v_and_b32_e32 v11, 24, v11
	v_sub_u32_e32 v1, v1, v2
	s_ashr_i32 s16, s12, 8
	s_lshl_b32 s5, s14, 10
	v_or3_b32 v4, v4, v5, v11
	v_lshlrev_b32_e32 v5, 5, v10
	v_ashrrev_i16_sdwa v1, v252, sext(v1) dst_sel:DWORD dst_unused:UNUSED_PAD src0_sel:DWORD src1_sel:BYTE_0
	v_readlane_b32 s8, v254, 37
	v_and_b32_e32 v5, 32, v5
	v_bfe_i32 v11, v1, 0, 16
	v_readlane_b32 s9, v254, 38
	s_add_u32 s22, s75, s8
	v_add_lshl_u32 v1, v5, v11, 1
	s_addc_u32 s23, s4, s9
	s_add_i32 s10, s5, 0
	v_lshl_add_u32 v168, v4, 11, v1
	s_add_i32 m0, s10, 0x10000
	v_lshl_add_u32 v170, v3, 11, v1
	global_load_lds_dwordx4 v168, s[22:23]
	s_add_i32 m0, s10, 0x12000
	s_add_u32 s8, s22, 0x40000
	global_load_lds_dwordx4 v14, s[22:23]
	s_addc_u32 s9, s23, 0
	s_add_i32 m0, s10, 0x14000
	s_add_i32 s11, s10, 0x2000
	global_load_lds_dwordx4 v168, s[8:9]
	s_add_i32 m0, s10, 0x16000
	s_add_i32 s26, s10, 0x4000
	global_load_lds_dwordx4 v14, s[8:9]
	v_readlane_b32 s8, v254, 43
	s_mov_b32 m0, s10
	v_readlane_b32 s9, v254, 44
	s_add_i32 s27, s10, 0x6000
	v_mov_b32_e32 v169, v0
	s_waitcnt vmcnt(4)
	v_mov_b32_e32 v15, v0
	s_cmp_eq_u32 s16, 1
	v_lshl_add_u64 v[2:3], s[22:23], 0, v[168:169]
	global_load_lds_dwordx4 v170, s[8:9]
	s_mov_b32 m0, s11
	v_lshl_add_u64 v[4:5], s[22:23], 0, v[14:15]
	global_load_lds_dwordx4 v166, s[8:9]
	v_readlane_b32 s8, v254, 45
	s_mov_b32 m0, s26
	v_readlane_b32 s9, v254, 46
	s_nop 4
	global_load_lds_dwordx4 v170, s[8:9]
	s_mov_b32 m0, s27
	s_nop 0
	global_load_lds_dwordx4 v166, s[8:9]
	s_cselect_b64 s[8:9], -1, 0
	s_cmp_lg_u32 s16, 1
	s_cbranch_scc1 .LBB0_179
	s_barrier

; #define PG8_STAGE(bufoff, gbase, voff) do { _Pragma("unroll") for (int _i = 0; _i < 2; ++_i) \
;         __builtin_amdgcn_global_load_lds((const unsigned*)((const char*)(gbase) + (voff)[_i]), (PG8_LAS unsigned*)(lds + (bufoff) + ldsw + _i * 8192), 16, 0, 0); } while (0)
; #define PG8_BAR __builtin_amdgcn_s_barrier()
; template <class Epi, class Sched, bool ALIGN_EPI = false, bool SP2 = false>
; __device__ __forceinline__ void gemm_phase(PG8_LAS unsigned char* lds, const Gemm g, const Sched& S, const Epi& E) {
;     int tid_ = mk_tid(); asm volatile("" : "+v"(tid_));
;     const int tid = tid_, wid = __builtin_amdgcn_readfirstlane(tid >> 6), lane = tid & 63, wr = wid >> 2, wc = wid & 3, fr = lane & 15, fq = lane >> 4;
;     const int K = g.K, nt = K / BK;
;     unsigned voffA[2], voffB[2];
; #pragma unroll
;     for (int i = 0; i < 2; ++i) { int R, C; stage_rc(tid * 16 + i * 8192, R, C); const int Rb = Epi::PERM ? ((R & ~31) + perm32(R & 31)) : R;
;         voffA[i] = (unsigned)(R * K + C) * 2u; voffB[i] = (unsigned)(Rb * K + C) * 2u; }
;     const size_t kstep = (size_t)(BK * 2);
;     const size_t hstep = (size_t)HALF * K * 2;
;     const size_t tstep = 2 * hstep;
;     const unsigned ldsw = (unsigned)wid * 1024u;
;     const int aoff = lds_byte(wr * 64 + fr, fq * 8), boff = lds_byte(wc * 32 + fr, fq * 8);
;     ...
;         PG8_STAGE(PG8_SB(0, 0), cB, voffB); PG8_STAGE(PG8_SB(0, 1), cB + hstep, voffB); PG8_STAGE(PG8_SA(0, 0), cA, voffA); PG8_STAGE(PG8_SA(0, 1), cA + hstep, voffA);
;         if (wr == 1) PG8_BAR;
.LBB0_771:
	s_waitcnt lgkmcnt(0)
	s_barrier
	s_getreg_b32 s8, hwreg(HW_REG_HW_ID, 0, 6)
	s_and_b32 s8, s8, 63
	s_lshl_b32 s8, s8, 2
	s_or_b32 s8, s8, 0x25000
	v_mov_b32_e32 v1, s8
	ds_read_b32 v1, v1
	v_mbcnt_lo_u32_b32 v2, -1, 0
	v_mbcnt_hi_u32_b32 v2, -1, v2
	s_waitcnt lgkmcnt(0)
	v_readfirstlane_b32 s8, v1
	s_waitcnt vmcnt(5)
	s_nop 0
	v_lshl_add_u32 v11, s8, 6, v2
	v_readlane_b32 s8, v254, 24
	v_readlane_b32 s9, v254, 25
	s_andn2_b64 vcc, exec, s[8:9]
	v_readfirstlane_b32 s14, v11
	s_cbranch_vccnz .LBB0_809
	v_lshlrev_b32_e32 v2, 4, v11
	v_add_u32_e32 v3, 0x2000, v2
	v_ashrrev_i32_e32 v1, 31, v3
	v_lshrrev_b32_e32 v1, 22, v1
	v_add_u32_e32 v1, v3, v1
	v_ashrrev_i32_e32 v1, 10, v1
	v_mul_i32_i24_e32 v4, 0x400, v1
	v_sub_u32_e32 v3, v3, v4
	v_lshrrev_b32_e32 v4, 4, v3
	v_bitop3_b32 v3, v4, v3, 32 bitop3:0x6c
	v_ashrrev_i32_e32 v4, 31, v3
	v_lshrrev_b32_e32 v4, 26, v4
	v_add_u32_e32 v4, v3, v4
	v_lshlrev_b32_e32 v5, 3, v1
	v_ashrrev_i32_e32 v6, 6, v4
	v_and_b32_e32 v5, -16, v5
	v_add_u32_e32 v5, v6, v5
	v_and_b32_e32 v7, 3, v6
	s_mov_b32 s8, 0x1fffe0
	v_lshrrev_b32_e32 v8, 2, v5
	v_lshlrev_b32_e32 v9, 1, v5
	v_and_b32_e32 v4, 0xc0, v4
	v_and_or_b32 v7, v5, s8, v7
	v_and_b32_e32 v8, 4, v8
	v_and_b32_e32 v9, 24, v9
	v_sub_u32_e32 v3, v3, v4
	v_or3_b32 v8, v7, v8, v9
	v_lshlrev_b32_e32 v7, 5, v1
	v_ashrrev_i16_sdwa v3, v252, sext(v3) dst_sel:DWORD dst_unused:UNUSED_PAD src0_sel:DWORD src1_sel:BYTE_0
	v_and_b32_e32 v9, 32, v7
	v_bfe_i32 v7, v3, 0, 16
	v_add_lshl_u32 v3, v9, v7, 1
	v_lshl_add_u32 v14, v8, 11, v3
	v_lshl_add_u32 v190, v5, 11, v3
	v_bfe_i32 v3, v11, 27, 1
	v_lshrrev_b32_e32 v3, 22, v3
	v_add_u32_e32 v3, v2, v3
	v_and_b32_e32 v3, 0xfffffc00, v3
	v_sub_u32_e32 v2, v2, v3
	v_lshrrev_b32_e32 v3, 4, v2
	v_ashrrev_i32_e32 v4, 31, v11
	v_bitop3_b32 v2, v3, v2, 32 bitop3:0x6c
	v_lshrrev_b32_e32 v4, 26, v4
	v_ashrrev_i32_e32 v3, 31, v2
	v_add_u32_e32 v4, v11, v4
	v_lshrrev_b32_e32 v3, 26, v3
	v_ashrrev_i32_e32 v9, 6, v4
	v_add_u32_e32 v3, v2, v3
	v_lshlrev_b32_e32 v4, 3, v9
	v_ashrrev_i32_e32 v8, 6, v3
	v_and_b32_e32 v4, -16, v4
	v_add_u32_e32 v4, v8, v4
	v_and_b32_e32 v5, 3, v8
	v_lshrrev_b32_e32 v10, 2, v4
	v_lshlrev_b32_e32 v12, 1, v4
	v_and_b32_e32 v3, 0xc0, v3
	s_ashr_i32 s15, s14, 6
	v_and_or_b32 v5, v4, s8, v5
	v_and_b32_e32 v10, 4, v10
	v_and_b32_e32 v12, 24, v12
	v_sub_u32_e32 v2, v2, v3
	s_ashr_i32 s12, s14, 8
	s_lshl_b32 s11, s15, 10
	v_or3_b32 v5, v5, v10, v12
	v_lshlrev_b32_e32 v10, 5, v9
	v_ashrrev_i16_sdwa v2, v252, sext(v2) dst_sel:DWORD dst_unused:UNUSED_PAD src0_sel:DWORD src1_sel:BYTE_0
	v_readlane_b32 s8, v254, 55
	v_and_b32_e32 v12, 32, v10
	v_bfe_i32 v10, v2, 0, 16
	v_readlane_b32 s9, v254, 56
	s_add_u32 s22, s5, s8
	v_add_lshl_u32 v2, v12, v10, 1
	s_addc_u32 s23, s10, s9
	s_add_i32 s28, s11, 0
	v_lshl_add_u32 v192, v5, 11, v2
	s_add_i32 m0, s28, 0x10000
	v_lshl_add_u32 v194, v4, 11, v2
	global_load_lds_dwordx4 v192, s[22:23]
	s_add_i32 m0, s28, 0x12000
	s_add_u32 s8, s22, 0x40000
	global_load_lds_dwordx4 v14, s[22:23]
	s_addc_u32 s9, s23, 0
	s_add_i32 m0, s28, 0x14000
	s_add_i32 s33, s28, 0x2000
	global_load_lds_dwordx4 v192, s[8:9]
	s_add_i32 m0, s28, 0x16000
	s_add_i32 s49, s28, 0x4000
	global_load_lds_dwordx4 v14, s[8:9]
	v_readlane_b32 s8, v254, 59
	s_mov_b32 m0, s28
	v_readlane_b32 s9, v254, 60
	s_add_i32 s71, s28, 0x6000
	v_mov_b32_e32 v193, v0
	s_waitcnt vmcnt(4)
	v_mov_b32_e32 v15, v0
	s_cmp_eq_u32 s12, 1
	v_lshl_add_u64 v[2:3], s[22:23], 0, v[192:193]
	global_load_lds_dwordx4 v194, s[8:9]
	s_mov_b32 m0, s33
	v_lshl_add_u64 v[4:5], s[22:23], 0, v[14:15]
	global_load_lds_dwordx4 v190, s[8:9]
	v_readlane_b32 s8, v254, 61
	s_mov_b32 m0, s49
	v_readlane_b32 s9, v254, 62
	s_nop 4
	global_load_lds_dwordx4 v194, s[8:9]
	s_mov_b32 m0, s71
	s_nop 0
	global_load_lds_dwordx4 v190, s[8:9]
	s_cselect_b64 s[8:9], -1, 0
	s_cmp_lg_u32 s12, 1
	s_cbranch_scc1 .LBB0_774
	s_barrier

; #define PG8_STAGE(bufoff, gbase, voff) do { _Pragma("unroll") for (int _i = 0; _i < 2; ++_i) \
;         __builtin_amdgcn_global_load_lds((const unsigned*)((const char*)(gbase) + (voff)[_i]), (PG8_LAS unsigned*)(lds + (bufoff) + ldsw + _i * 8192), 16, 0, 0); } while (0)
; #define PG8_BAR __builtin_amdgcn_s_barrier()
; template <class Epi, class Sched, bool ALIGN_EPI = false, bool SP2 = false>
; __device__ __forceinline__ void gemm_phase(PG8_LAS unsigned char* lds, const Gemm g, const Sched& S, const Epi& E) {
;     int tid_ = mk_tid(); asm volatile("" : "+v"(tid_));
;     const int tid = tid_, wid = __builtin_amdgcn_readfirstlane(tid >> 6), lane = tid & 63, wr = wid >> 2, wc = wid & 3, fr = lane & 15, fq = lane >> 4;
;     const int K = g.K, nt = K / BK;
;     unsigned voffA[2], voffB[2];
; #pragma unroll
;     for (int i = 0; i < 2; ++i) { int R, C; stage_rc(tid * 16 + i * 8192, R, C); const int Rb = Epi::PERM ? ((R & ~31) + perm32(R & 31)) : R;
;         voffA[i] = (unsigned)(R * K + C) * 2u; voffB[i] = (unsigned)(Rb * K + C) * 2u; }
;     const size_t kstep = (size_t)(BK * 2);
;     const size_t hstep = (size_t)HALF * K * 2;
;     const size_t tstep = 2 * hstep;
;     const unsigned ldsw = (unsigned)wid * 1024u;
;     const int aoff = lds_byte(wr * 64 + fr, fq * 8), boff = lds_byte(wc * 32 + fr, fq * 8);
;     ...
;         PG8_STAGE(PG8_SB(0, 0), cB, voffB); PG8_STAGE(PG8_SB(0, 1), cB + hstep, voffB); PG8_STAGE(PG8_SA(0, 0), cA, voffA); PG8_STAGE(PG8_SA(0, 1), cA + hstep, voffA);
;         if (wr == 1) PG8_BAR;
.LBB0_973:
	s_waitcnt lgkmcnt(0)
	s_barrier
	s_getreg_b32 s5, hwreg(HW_REG_HW_ID, 0, 6)
	s_and_b32 s5, s5, 63
	s_lshl_b32 s5, s5, 2
	s_or_b32 s5, s5, 0x25000
	v_mov_b32_e32 v1, s5
	ds_read_b32 v1, v1
	v_readlane_b32 s8, v254, 20
	v_mbcnt_lo_u32_b32 v2, -1, 0
	v_mbcnt_hi_u32_b32 v2, -1, v2
	v_readlane_b32 s9, v254, 21
	s_andn2_b64 vcc, exec, s[8:9]
	s_waitcnt lgkmcnt(0)
	v_readfirstlane_b32 s5, v1
	s_waitcnt vmcnt(5)
	s_nop 0
	v_lshl_add_u32 v12, s5, 6, v2
	s_nop 0
	v_readfirstlane_b32 s14, v12
	s_cbranch_vccnz .LBB0_995
	v_lshlrev_b32_e32 v1, 4, v12
	v_add_u32_e32 v2, 0x2000, v1
	v_ashrrev_i32_e32 v3, 31, v2
	v_lshrrev_b32_e32 v3, 22, v3
	v_add_u32_e32 v3, v2, v3
	v_ashrrev_i32_e32 v6, 10, v3
	v_mul_i32_i24_e32 v3, 0x400, v6
	v_sub_u32_e32 v2, v2, v3
	v_lshrrev_b32_e32 v3, 4, v2
	v_bitop3_b32 v2, v3, v2, 32 bitop3:0x6c
	v_ashrrev_i32_e32 v3, 31, v2
	v_lshrrev_b32_e32 v3, 26, v3
	v_add_u32_e32 v3, v2, v3
	v_lshlrev_b32_e32 v4, 3, v6
	v_ashrrev_i32_e32 v7, 6, v3
	v_and_b32_e32 v4, -16, v4
	v_add_u32_e32 v4, v7, v4
	v_and_b32_e32 v5, 3, v7
	s_mov_b32 s8, 0x1fffe0
	v_lshrrev_b32_e32 v8, 2, v4
	v_lshlrev_b32_e32 v9, 1, v4
	v_and_b32_e32 v3, 0xc0, v3
	v_and_or_b32 v5, v4, s8, v5
	v_and_b32_e32 v8, 4, v8
	v_and_b32_e32 v9, 24, v9
	v_sub_u32_e32 v2, v2, v3
	v_or3_b32 v5, v5, v8, v9
	v_lshlrev_b32_e32 v8, 5, v6
	v_ashrrev_i16_sdwa v2, v252, sext(v2) dst_sel:DWORD dst_unused:UNUSED_PAD src0_sel:DWORD src1_sel:BYTE_0
	v_and_b32_e32 v9, 32, v8
	v_bfe_i32 v8, v2, 0, 16
	v_add_lshl_u32 v2, v9, v8, 1
	v_lshl_add_u32 v14, v5, 11, v2
	v_lshl_add_u32 v166, v4, 11, v2
	v_bfe_i32 v2, v12, 27, 1
	v_lshrrev_b32_e32 v2, 22, v2
	v_add_u32_e32 v2, v1, v2
	v_and_b32_e32 v2, 0xfffffc00, v2
	v_sub_u32_e32 v1, v1, v2
	v_lshrrev_b32_e32 v2, 4, v1
	v_ashrrev_i32_e32 v3, 31, v12
	v_bitop3_b32 v1, v2, v1, 32 bitop3:0x6c
	v_lshrrev_b32_e32 v3, 26, v3
	v_ashrrev_i32_e32 v2, 31, v1
	v_add_u32_e32 v3, v12, v3
	v_lshrrev_b32_e32 v2, 26, v2
	v_ashrrev_i32_e32 v10, 6, v3
	v_add_u32_e32 v2, v1, v2
	v_lshlrev_b32_e32 v3, 3, v10
	v_ashrrev_i32_e32 v9, 6, v2
	v_and_b32_e32 v3, -16, v3
	s_ashr_i32 s15, s14, 6
	v_add_u32_e32 v3, v9, v3
	s_ashr_i32 s12, s14, 8
	s_lshl_b32 s5, s15, 10
	v_and_b32_e32 v4, 3, v9
	v_lshrrev_b32_e32 v5, 2, v3
	v_lshlrev_b32_e32 v11, 1, v3
	v_and_b32_e32 v2, 0xc0, v2
	s_add_u32 s10, s75, 0x800000
	v_and_or_b32 v4, v3, s8, v4
	v_and_b32_e32 v5, 4, v5
	v_and_b32_e32 v11, 24, v11
	v_sub_u32_e32 v1, v1, v2
	s_addc_u32 s11, s4, 0
	v_or3_b32 v4, v4, v5, v11
	v_lshlrev_b32_e32 v5, 5, v10
	v_ashrrev_i16_sdwa v1, v252, sext(v1) dst_sel:DWORD dst_unused:UNUSED_PAD src0_sel:DWORD src1_sel:BYTE_0
	v_readlane_b32 s8, v254, 27
	v_and_b32_e32 v5, 32, v5
	v_bfe_i32 v11, v1, 0, 16
	v_readlane_b32 s9, v254, 28
	s_add_u32 s22, s10, s8
	v_add_lshl_u32 v1, v5, v11, 1
	s_addc_u32 s23, s11, s9
	s_add_i32 s20, s5, 0
	v_lshl_add_u32 v168, v4, 11, v1
	s_add_i32 m0, s20, 0x10000
	v_lshl_add_u32 v170, v3, 11, v1
	global_load_lds_dwordx4 v168, s[22:23]
	s_add_i32 m0, s20, 0x12000
	s_add_u32 s8, s22, 0x40000
	global_load_lds_dwordx4 v14, s[22:23]
	s_addc_u32 s9, s23, 0
	s_add_i32 m0, s20, 0x14000
	s_add_i32 s26, s20, 0x2000
	global_load_lds_dwordx4 v168, s[8:9]
	s_add_i32 m0, s20, 0x16000
	s_add_i32 s27, s20, 0x4000
	global_load_lds_dwordx4 v14, s[8:9]
	v_readlane_b32 s8, v254, 33
	s_mov_b32 m0, s20
	v_readlane_b32 s9, v254, 34
	s_add_i32 s28, s20, 0x6000
	v_mov_b32_e32 v169, v0
	s_waitcnt vmcnt(4)
	v_mov_b32_e32 v15, v0
	s_cmp_eq_u32 s12, 1
	v_lshl_add_u64 v[2:3], s[22:23], 0, v[168:169]
	global_load_lds_dwordx4 v170, s[8:9]
	s_mov_b32 m0, s26
	v_lshl_add_u64 v[4:5], s[22:23], 0, v[14:15]
	global_load_lds_dwordx4 v166, s[8:9]
	v_readlane_b32 s8, v254, 35
	s_mov_b32 m0, s27
	v_readlane_b32 s9, v254, 36
	s_nop 4
	global_load_lds_dwordx4 v170, s[8:9]
	s_mov_b32 m0, s28
	s_nop 0
	global_load_lds_dwordx4 v166, s[8:9]
	s_cselect_b64 s[8:9], -1, 0
	s_cmp_lg_u32 s12, 1
	s_cbranch_scc1 .LBB0_976
	s_barrier

; #define PG8_STAGE(bufoff, gbase, voff) do { _Pragma("unroll") for (int _i = 0; _i < 2; ++_i) \
;         __builtin_amdgcn_global_load_lds((const unsigned*)((const char*)(gbase) + (voff)[_i]), (PG8_LAS unsigned*)(lds + (bufoff) + ldsw + _i * 8192), 16, 0, 0); } while (0)
; #define PG8_BAR __builtin_amdgcn_s_barrier()
; template <class Epi, class Sched, bool ALIGN_EPI = false, bool SP2 = false>
; __device__ __forceinline__ void gemm_phase(PG8_LAS unsigned char* lds, const Gemm g, const Sched& S, const Epi& E) {
;     int tid_ = mk_tid(); asm volatile("" : "+v"(tid_));
;     const int tid = tid_, wid = __builtin_amdgcn_readfirstlane(tid >> 6), lane = tid & 63, wr = wid >> 2, wc = wid & 3, fr = lane & 15, fq = lane >> 4;
;     const int K = g.K, nt = K / BK;
;     unsigned voffA[2], voffB[2];
; #pragma unroll
;     for (int i = 0; i < 2; ++i) { int R, C; stage_rc(tid * 16 + i * 8192, R, C); const int Rb = Epi::PERM ? ((R & ~31) + perm32(R & 31)) : R;
;         voffA[i] = (unsigned)(R * K + C) * 2u; voffB[i] = (unsigned)(Rb * K + C) * 2u; }
;     const size_t kstep = (size_t)(BK * 2);
;     const size_t hstep = (size_t)HALF * K * 2;
;     const size_t tstep = 2 * hstep;
;     const unsigned ldsw = (unsigned)wid * 1024u;
;     const int aoff = lds_byte(wr * 64 + fr, fq * 8), boff = lds_byte(wc * 32 + fr, fq * 8);
;     ...
;         PG8_STAGE(PG8_SB(0, 0), cB, voffB); PG8_STAGE(PG8_SB(0, 1), cB + hstep, voffB); PG8_STAGE(PG8_SA(0, 0), cA, voffA); PG8_STAGE(PG8_SA(0, 1), cA + hstep, voffA);
;         if (wr == 1) PG8_BAR;
.LBB0_1121:
	s_waitcnt lgkmcnt(0)
	s_barrier
	s_getreg_b32 s5, hwreg(HW_REG_HW_ID, 0, 6)
	s_and_b32 s5, s5, 63
	s_lshl_b32 s5, s5, 2
	s_or_b32 s5, s5, 0x25000
	v_mov_b32_e32 v1, s5
	ds_read_b32 v1, v1
	v_readlane_b32 s8, v254, 24
	v_mbcnt_lo_u32_b32 v2, -1, 0
	v_mbcnt_hi_u32_b32 v2, -1, v2
	v_readlane_b32 s9, v254, 25
	s_andn2_b64 vcc, exec, s[8:9]
	s_waitcnt lgkmcnt(0)
	v_readfirstlane_b32 s5, v1
	s_waitcnt vmcnt(5)
	s_nop 0
	v_lshl_add_u32 v11, s5, 6, v2
	s_nop 0
	v_readfirstlane_b32 s16, v11
	s_cbranch_vccnz .LBB0_1159
	v_lshlrev_b32_e32 v2, 4, v11
	v_add_u32_e32 v3, 0x2000, v2
	v_ashrrev_i32_e32 v1, 31, v3
	v_lshrrev_b32_e32 v1, 22, v1
	v_add_u32_e32 v1, v3, v1
	v_ashrrev_i32_e32 v1, 10, v1
	v_mul_i32_i24_e32 v4, 0x400, v1
	v_sub_u32_e32 v3, v3, v4
	v_lshrrev_b32_e32 v4, 4, v3
	v_bitop3_b32 v3, v4, v3, 32 bitop3:0x6c
	v_ashrrev_i32_e32 v4, 31, v3
	v_lshrrev_b32_e32 v4, 26, v4
	v_add_u32_e32 v4, v3, v4
	v_lshlrev_b32_e32 v5, 3, v1
	v_ashrrev_i32_e32 v6, 6, v4
	v_and_b32_e32 v5, -16, v5
	v_add_u32_e32 v5, v6, v5
	v_and_b32_e32 v7, 3, v6
	s_mov_b32 s8, 0x7ffe0
	v_lshrrev_b32_e32 v8, 2, v5
	v_lshlrev_b32_e32 v9, 1, v5
	v_and_b32_e32 v4, 0xc0, v4
	v_and_or_b32 v7, v5, s8, v7
	v_and_b32_e32 v8, 4, v8
	v_and_b32_e32 v9, 24, v9
	v_sub_u32_e32 v3, v3, v4
	v_or3_b32 v8, v7, v8, v9
	v_lshlrev_b32_e32 v7, 5, v1
	v_ashrrev_i16_sdwa v3, v252, sext(v3) dst_sel:DWORD dst_unused:UNUSED_PAD src0_sel:DWORD src1_sel:BYTE_0
	v_and_b32_e32 v9, 32, v7
	v_bfe_i32 v7, v3, 0, 16
	v_add_lshl_u32 v3, v9, v7, 1
	v_lshl_add_u32 v14, v8, 13, v3
	v_lshl_add_u32 v190, v5, 13, v3
	v_bfe_i32 v3, v11, 27, 1
	v_lshrrev_b32_e32 v3, 22, v3
	v_add_u32_e32 v3, v2, v3
	v_and_b32_e32 v3, 0xfffffc00, v3
	v_sub_u32_e32 v2, v2, v3
	v_lshrrev_b32_e32 v3, 4, v2
	v_ashrrev_i32_e32 v4, 31, v11
	v_bitop3_b32 v2, v3, v2, 32 bitop3:0x6c
	v_lshrrev_b32_e32 v4, 26, v4
	v_ashrrev_i32_e32 v3, 31, v2
	v_add_u32_e32 v4, v11, v4
	v_lshrrev_b32_e32 v3, 26, v3
	v_ashrrev_i32_e32 v9, 6, v4
	v_add_u32_e32 v3, v2, v3
	v_lshlrev_b32_e32 v4, 3, v9
	v_ashrrev_i32_e32 v8, 6, v3
	v_and_b32_e32 v4, -16, v4
	s_ashr_i32 s17, s16, 6
	v_add_u32_e32 v4, v8, v4
	s_ashr_i32 s12, s16, 8
	s_lshl_b32 s5, s17, 10
	v_and_b32_e32 v5, 3, v8
	v_lshrrev_b32_e32 v10, 2, v4
	v_lshlrev_b32_e32 v12, 1, v4
	v_and_b32_e32 v3, 0xc0, v3
	s_add_u32 s10, s75, 0x1000000
	v_and_or_b32 v5, v4, s8, v5
	v_and_b32_e32 v10, 4, v10
	v_and_b32_e32 v12, 24, v12
	v_sub_u32_e32 v2, v2, v3
	s_addc_u32 s4, s4, 0
	v_or3_b32 v5, v5, v10, v12
	v_lshlrev_b32_e32 v10, 5, v9
	v_ashrrev_i16_sdwa v2, v252, sext(v2) dst_sel:DWORD dst_unused:UNUSED_PAD src0_sel:DWORD src1_sel:BYTE_0
	v_readlane_b32 s8, v254, 63
	v_and_b32_e32 v12, 32, v10
	v_bfe_i32 v10, v2, 0, 16
	v_readlane_b32 s9, v255, 0
	s_add_u32 s22, s10, s8
	v_add_lshl_u32 v2, v12, v10, 1
	s_addc_u32 s23, s4, s9
	s_add_i32 s11, s5, 0
	v_lshl_add_u32 v192, v5, 13, v2
	s_add_i32 m0, s11, 0x10000
	v_lshl_add_u32 v194, v4, 13, v2
	global_load_lds_dwordx4 v192, s[22:23]
	s_add_i32 m0, s11, 0x12000
	s_add_u32 s8, s22, 0x100000
	global_load_lds_dwordx4 v14, s[22:23]
	s_addc_u32 s9, s23, 0
	s_add_i32 m0, s11, 0x14000
	s_add_i32 s28, s11, 0x2000
	global_load_lds_dwordx4 v192, s[8:9]
	s_add_i32 m0, s11, 0x16000
	s_add_i32 s33, s11, 0x4000
	global_load_lds_dwordx4 v14, s[8:9]
	v_readlane_b32 s8, v255, 3
	s_mov_b32 m0, s11
	v_readlane_b32 s9, v255, 4
	s_add_i32 s49, s11, 0x6000
	v_mov_b32_e32 v193, v0
	s_waitcnt vmcnt(4)
	v_mov_b32_e32 v15, v0
	s_cmp_eq_u32 s12, 1
	v_lshl_add_u64 v[2:3], s[22:23], 0, v[192:193]
	global_load_lds_dwordx4 v194, s[8:9]
	s_mov_b32 m0, s28
	v_lshl_add_u64 v[4:5], s[22:23], 0, v[14:15]
	global_load_lds_dwordx4 v190, s[8:9]
	v_readlane_b32 s8, v255, 5
	s_mov_b32 m0, s33
	v_readlane_b32 s9, v255, 6
	s_nop 4
	global_load_lds_dwordx4 v194, s[8:9]
	s_mov_b32 m0, s49
	s_nop 0
	global_load_lds_dwordx4 v190, s[8:9]
	s_cselect_b64 s[8:9], -1, 0
	s_cmp_lg_u32 s12, 1
	s_cbranch_scc1 .LBB0_1124
	s_barrier
